# LayerNorm row loops: packed f32 ops on v_mov-gathered pairs replaced by the two scalar ops on the original registers (dead copies dropped); LN1 butterflies reuse the precomputed xor addresses
# speedup vs baseline: 1.0025x; 1.0025x over previous
; DI float bflo(uint32_t u) { return __uint_as_float(u << 16); }
; template <int SRC, bool Q8, bool OUTF>
; DI void ln_rows(const void* __restrict__ srcv, const u16* res, u16* dstb, uint32_t* __restrict__ dstq, float* __restrict__ xsc, float* __restrict__ dstf,
;                 const float* __restrict__ g, const float* __restrict__ b, int nrows, const int WAVE_S) {
;     ...
;   auto load = [&](int row, u32x4 (&sa)[NR], u32x4 (&ra)[2]) {
;     row = row < nrows ? row : nrows - 1;
;     if (SRC == 0) {
;       const float* sp = (const float*)srcv + (size_t)row * DM + 8 * lane;
; #pragma unroll
;       for (int i = 0; i < 2; ++i) { sa[2 * i] = *(const u32x4*)(sp + 512 * i); sa[2 * i + 1] = *(const u32x4*)(sp + 512 * i + 4); }
;     } else {
;       const u16* sp = (const u16*)srcv + (size_t)row * DM + 8 * lane;
;       const u16* rp = res + (size_t)row * DM + 8 * lane;
; #pragma unroll
;       for (int i = 0; i < 2; ++i) { sa[i] = *(const u32x4*)(sp + 512 * i); ra[i] = *(const u32x4*)(rp + 512 * i); }
;     }
;   };
;   auto process = [&](int row, const u32x4 (&sa)[NR], const u32x4 (&ra)[2]) {
;     f32x4 v[4];
;     if (SRC == 0) {
; #pragma unroll
;       for (int q = 0; q < 4; ++q) v[q] = __builtin_bit_cast(f32x4, sa[q]);
;     } else {
; #pragma unroll
;       for (int i = 0; i < 2; ++i)
; #pragma unroll
;         for (int hh = 0; hh < 2; ++hh) {
;           const uint32_t s0 = sa[i][2 * hh], s1 = sa[i][2 * hh + 1], r0 = ra[i][2 * hh], r1 = ra[i][2 * hh + 1];
;           v[2 * i + hh] = (f32x4){ALPHA * bflo(r0) + bflo(s0), ALPHA * bfhi(r0) + bfhi(s0), ALPHA * bflo(r1) + bflo(s1), ALPHA * bfhi(r1) + bfhi(s1)};
;         }
;     }
;     float sum = 0.f;
; #pragma unroll
;     for (int q = 0; q < 4; ++q) sum += v[q][0] + v[q][1] + v[q][2] + v[q][3];
;     const float mu = wave_sum(sum) * (1.f / DM);
;     float sq = 0.f;
; #pragma unroll
;     for (int q = 0; q < 4; ++q) {
;       v[q] -= mu;
;       sq += v[q][0] * v[q][0] + v[q][1] * v[q][1] + v[q][2] * v[q][2] + v[q][3] * v[q][3];
;     }
;     const float rstd = rsqrtf(wave_sum(sq) * (1.f / DM) + 1e-5f);
;     float am = 0.f;
; #pragma unroll
;     for (int q = 0; q < 4; ++q) {
;       v[q] = v[q] * rstd * g4[q] + b4[q];
;       if (Q8) am = fmaxf(am, fmaxf(fmaxf(fabsf(v[q][0]), fabsf(v[q][1])), fmaxf(fabsf(v[q][2]), fabsf(v[q][3]))));
;     }
; #pragma unroll
;     for (int i = 0; i < 2; ++i) {
.LBB0_9:
	v_add_u32_e32 v74, s64, v76
	s_waitcnt vmcnt(2)
	v_min_i32_e32 v46, 0xffff, v74
	v_ashrrev_i32_e32 v47, 31, v46
	v_lshlrev_b64 v[46:47], 12, v[46:47]
	v_lshl_add_u64 v[66:67], v[70:71], 0, v[46:47]
	global_load_dwordx4 v[50:53], v[66:67], off offset:16
	global_load_dwordx4 v[46:49], v[66:67], off
	global_load_dwordx4 v[58:61], v[66:67], off offset:2064
	global_load_dwordx4 v[54:57], v[66:67], off offset:2048
	v_pk_add_f32 v[66:67], v[38:39], v[62:63]
	s_waitcnt vmcnt(4)
	v_mov_b32_e32 v80, v42
	v_pk_add_f32 v[66:67], v[66:67], v[40:41]
	v_mov_b32_e32 v78, v44
	v_pk_add_f32 v[66:67], v[66:67], v[64:65]
	s_waitcnt lgkmcnt(0)
	v_mov_b32_e32 v36, v45
	v_add_f32_e32 v34, 0, v67
	v_add_f32_e32 v68, v66, v34
	v_mov_b32_e32 v34, v43
	v_add_f32_e32 v66, v80, v43
	v_add_f32_e32 v67, v81, v35
	s_and_b64 vcc, exec, s[4:5]
	v_pk_add_f32 v[66:67], v[78:79], v[66:67]
	s_nop 0
	v_pk_add_f32 v[66:67], v[36:37], v[66:67]
	v_mbcnt_lo_u32_b32 v36, -1, 0
	v_mbcnt_hi_u32_b32 v36, -1, v36
	s_nop 0
	v_add_f32_e32 v34, v67, v68
	v_lshlrev_b32_e32 v36, 2, v36
	v_add_f32_e32 v34, v66, v34
	v_xor_b32_e32 v66, 0x80, v36
	ds_bpermute_b32 v66, v66, v34
	s_waitcnt lgkmcnt(0)
	v_add_f32_e32 v34, v34, v66
	v_xor_b32_e32 v66, 64, v36
	ds_bpermute_b32 v66, v66, v34
	s_waitcnt lgkmcnt(0)
	v_add_f32_e32 v34, v34, v66
	v_xor_b32_e32 v66, 32, v36
	ds_bpermute_b32 v66, v66, v34
	s_waitcnt lgkmcnt(0)
	v_add_f32_e32 v34, v34, v66
	v_xor_b32_e32 v66, 16, v36
	ds_bpermute_b32 v66, v66, v34
	s_waitcnt lgkmcnt(0)
	v_add_f32_e32 v34, v34, v66
	v_xor_b32_e32 v66, 8, v36
	ds_bpermute_b32 v66, v66, v34
	v_xor_b32_e32 v36, 4, v36
	s_waitcnt lgkmcnt(0)
	v_add_f32_e32 v34, v34, v66
	ds_bpermute_b32 v36, v36, v34
	s_waitcnt lgkmcnt(0)
	v_add_f32_e32 v34, v34, v36
	v_fmac_f32_e32 v63, 0xba800000, v34
	v_fmac_f32_e32 v62, 0xba800000, v34
	v_fmac_f32_e32 v39, 0xba800000, v34
	v_mul_f32_e32 v36, v63, v63
	v_fmac_f32_e32 v38, 0xba800000, v34
	v_mul_f32_e32 v66, v62, v62
	v_fmac_f32_e32 v41, 0xba800000, v34
	v_fmac_f32_e32 v36, v39, v39
	v_fmac_f32_e32 v40, 0xba800000, v34
	v_fmac_f32_e32 v66, v38, v38
	v_fmac_f32_e32 v65, 0xba800000, v34
	v_fmac_f32_e32 v36, v41, v41
	v_fmac_f32_e32 v64, 0xba800000, v34
	v_fmac_f32_e32 v66, v40, v40
	v_fmac_f32_e32 v36, v65, v65
	v_fmac_f32_e32 v66, v64, v64
	v_fmac_f32_e32 v35, 0xba800000, v34
	v_add_f32_e32 v36, v36, v66
	v_fmac_f32_e32 v81, 0xba800000, v34
	v_mul_f32_e32 v66, v35, v35
	v_fmamk_f32 v43, v34, 0xba800000, v43
	v_fmac_f32_e32 v37, 0xba800000, v34
	v_fmac_f32_e32 v79, 0xba800000, v34
	v_fmac_f32_e32 v66, v81, v81
	v_fmamk_f32 v45, v34, 0xba800000, v45
	v_fmamk_f32 v44, v34, 0xba800000, v44
	v_fmac_f32_e32 v42, 0xba800000, v34
	v_mul_f32_e32 v34, v43, v43
	v_fmac_f32_e32 v66, v79, v79
	v_fmac_f32_e32 v34, v42, v42
	v_fmac_f32_e32 v66, v37, v37
	v_fmac_f32_e32 v34, v44, v44
	v_add_f32_e32 v36, v66, v36
	v_fmac_f32_e32 v34, v45, v45
	v_add_f32_e32 v34, v34, v36
	v_mbcnt_lo_u32_b32 v36, -1, 0
	v_mbcnt_hi_u32_b32 v36, -1, v36
	s_nop 0
	v_lshlrev_b32_e32 v36, 2, v36
	v_xor_b32_e32 v66, 0x80, v36
	ds_bpermute_b32 v66, v66, v34
	s_waitcnt lgkmcnt(0)
	v_add_f32_e32 v34, v34, v66
	v_xor_b32_e32 v66, 64, v36
	ds_bpermute_b32 v66, v66, v34
	s_waitcnt lgkmcnt(0)
	v_add_f32_e32 v34, v34, v66
	v_xor_b32_e32 v66, 32, v36
	ds_bpermute_b32 v66, v66, v34
	s_waitcnt lgkmcnt(0)
	v_add_f32_e32 v34, v34, v66
	v_xor_b32_e32 v66, 16, v36
	ds_bpermute_b32 v66, v66, v34
	s_waitcnt lgkmcnt(0)
	v_add_f32_e32 v34, v34, v66
	v_xor_b32_e32 v66, 8, v36
	ds_bpermute_b32 v66, v66, v34
	v_xor_b32_e32 v36, 4, v36
	s_waitcnt lgkmcnt(0)
	v_add_f32_e32 v34, v34, v66
	ds_bpermute_b32 v36, v36, v34
	s_cbranch_vccnz .LBB0_11
	s_waitcnt lgkmcnt(0)
	v_add_f32_e32 v34, v34, v36
	v_fmamk_f32 v34, v34, 0x3a800000, v82
	v_mul_f32_e32 v36, 0x4b800000, v34
	v_cmp_gt_f32_e32 vcc, s17, v34
	v_mov_b32_e32 v66, v39
	v_mov_b32_e32 v39, v62
	v_cndmask_b32_e32 v34, v34, v36, vcc
	v_rsq_f32_e32 v36, v34
	v_mov_b32_e32 v34, v81
	v_mov_b32_e32 v67, v63
	v_ashrrev_i32_e32 v77, 31, v76
	v_mul_f32_e32 v68, 0x45800000, v36
	v_cndmask_b32_e32 v68, v36, v68, vcc
	v_mov_b32_e32 v36, v79
	v_pk_mul_f32 v[36:37], v[36:37], v[68:69] op_sel_hi:[1,0]
	v_pk_mul_f32 v[34:35], v[34:35], v[68:69] op_sel_hi:[1,0]
	v_pk_fma_f32 v[80:81], v[28:29], v[36:37], v[32:33]
	v_pk_fma_f32 v[78:79], v[26:27], v[34:35], v[30:31]
	v_mov_b32_e32 v34, v40
	v_mov_b32_e32 v35, v64
	v_pk_mul_f32 v[36:37], v[38:39], v[68:69] op_sel_hi:[1,0]
	v_mov_b32_e32 v64, v41
	v_pk_mul_f32 v[34:35], v[34:35], v[68:69] op_sel_hi:[1,0]
	v_pk_fma_f32 v[38:39], v[2:3], v[36:37], v[6:7]
	v_pk_mul_f32 v[36:37], v[64:65], v[68:69] op_sel_hi:[1,0]
	v_pk_mul_f32 v[40:41], v[66:67], v[68:69] op_sel_hi:[1,0]
	v_lshlrev_b64 v[62:63], 11, v[76:77]
	v_pk_mul_f32 v[44:45], v[44:45], v[68:69] op_sel_hi:[1,0]
	v_pk_mul_f32 v[42:43], v[42:43], v[68:69] op_sel_hi:[1,0]
	v_pk_fma_f32 v[34:35], v[4:5], v[34:35], v[8:9]
	v_pk_fma_f32 v[40:41], v[10:11], v[40:41], v[14:15]
	v_pk_fma_f32 v[64:65], v[12:13], v[36:37], v[16:17]
	v_pk_fma_f32 v[42:43], v[18:19], v[42:43], v[22:23]
	v_pk_fma_f32 v[44:45], v[20:21], v[44:45], v[24:25]
	v_cvt_pk_bf16_f32 v37, v34, v35
	v_cvt_pk_bf16_f32 v36, v38, v39
	v_cvt_pk_bf16_f32 v35, v64, v65
	v_cvt_pk_bf16_f32 v34, v40, v41
	v_lshl_add_u64 v[38:39], v[72:73], 0, v[62:63]
	global_store_dwordx4 v[38:39], v[34:37], off
	s_nop 1
	v_cvt_pk_bf16_f32 v37, v44, v45
	v_cvt_pk_bf16_f32 v36, v42, v43
	v_cvt_pk_bf16_f32 v35, v80, v81
	v_cvt_pk_bf16_f32 v34, v78, v79
	global_store_dwordx4 v[38:39], v[34:37], off offset:1024
; DI float bflo(uint32_t u) { return __uint_as_float(u << 16); }
; template <int SRC, bool Q8, bool OUTF>
; DI void ln_rows(const void* __restrict__ srcv, const u16* res, u16* dstb, uint32_t* __restrict__ dstq, float* __restrict__ xsc, float* __restrict__ dstf,
;                 const float* __restrict__ g, const float* __restrict__ b, int nrows, const int WAVE_S) {
;     ...
;   auto load = [&](int row, u32x4 (&sa)[NR], u32x4 (&ra)[2]) {
;     row = row < nrows ? row : nrows - 1;
;     if (SRC == 0) {
;       const float* sp = (const float*)srcv + (size_t)row * DM + 8 * lane;
; #pragma unroll
;       for (int i = 0; i < 2; ++i) { sa[2 * i] = *(const u32x4*)(sp + 512 * i); sa[2 * i + 1] = *(const u32x4*)(sp + 512 * i + 4); }
;     } else {
;       const u16* sp = (const u16*)srcv + (size_t)row * DM + 8 * lane;
;       const u16* rp = res + (size_t)row * DM + 8 * lane;
; #pragma unroll
;       for (int i = 0; i < 2; ++i) { sa[i] = *(const u32x4*)(sp + 512 * i); ra[i] = *(const u32x4*)(rp + 512 * i); }
;     }
;   };
;   auto process = [&](int row, const u32x4 (&sa)[NR], const u32x4 (&ra)[2]) {
;     f32x4 v[4];
;     if (SRC == 0) {
; #pragma unroll
;       for (int q = 0; q < 4; ++q) v[q] = __builtin_bit_cast(f32x4, sa[q]);
;     } else {
; #pragma unroll
;       for (int i = 0; i < 2; ++i)
; #pragma unroll
;         for (int hh = 0; hh < 2; ++hh) {
;           const uint32_t s0 = sa[i][2 * hh], s1 = sa[i][2 * hh + 1], r0 = ra[i][2 * hh], r1 = ra[i][2 * hh + 1];
;           v[2 * i + hh] = (f32x4){ALPHA * bflo(r0) + bflo(s0), ALPHA * bfhi(r0) + bfhi(s0), ALPHA * bflo(r1) + bflo(s1), ALPHA * bfhi(r1) + bfhi(s1)};
;         }
;     }
;     float sum = 0.f;
; #pragma unroll
;     for (int q = 0; q < 4; ++q) sum += v[q][0] + v[q][1] + v[q][2] + v[q][3];
;     const float mu = wave_sum(sum) * (1.f / DM);
;     float sq = 0.f;
; #pragma unroll
;     for (int q = 0; q < 4; ++q) {
;       v[q] -= mu;
;       sq += v[q][0] * v[q][0] + v[q][1] * v[q][1] + v[q][2] * v[q][2] + v[q][3] * v[q][3];
;     }
;     const float rstd = rsqrtf(wave_sum(sq) * (1.f / DM) + 1e-5f);
;     float am = 0.f;
; #pragma unroll
;     for (int q = 0; q < 4; ++q) {
;       v[q] = v[q] * rstd * g4[q] + b4[q];
;       if (Q8) am = fmaxf(am, fmaxf(fmaxf(fabsf(v[q][0]), fabsf(v[q][1])), fmaxf(fabsf(v[q][2]), fabsf(v[q][3]))));
;     }
; #pragma unroll
;     for (int i = 0; i < 2; ++i) {
.LBB0_11:
	v_cmp_gt_i32_e32 vcc, s18, v74
	s_mov_b64 s[14:15], -1
	s_and_saveexec_b64 s[12:13], vcc
	s_cbranch_execz .LBB0_8
	v_add_u32_e32 v34, s19, v76
	v_min_i32_e32 v34, 0xffff, v34
	v_ashrrev_i32_e32 v35, 31, v34
	v_lshlrev_b64 v[34:35], 12, v[34:35]
	v_lshl_add_u64 v[62:63], v[70:71], 0, v[34:35]
	global_load_dwordx4 v[38:41], v[62:63], off offset:16
	global_load_dwordx4 v[66:69], v[62:63], off
	global_load_dwordx4 v[42:45], v[62:63], off offset:2064
	s_waitcnt lgkmcnt(0)
	global_load_dwordx4 v[34:37], v[62:63], off offset:2048
	s_waitcnt vmcnt(6)
	v_add_f32_e32 v62, v46, v47
	v_add_f32_e32 v63, v50, v51
	v_add_f32_e32 v62, v48, v62
	v_add_f32_e32 v63, v52, v63
	v_mov_b32_e32 v64, v49
	v_mov_b32_e32 v65, v53
	v_add_f32_e32 v62, v49, v62
	v_add_f32_e32 v63, v53, v63
	s_waitcnt vmcnt(4)
	v_add_f32_e32 v62, 0, v62
	v_add_f32_e32 v75, v62, v63
	v_add_f32_e32 v62, v54, v55
	v_add_f32_e32 v63, v58, v59
	v_add_f32_e32 v62, v56, v62
	v_add_f32_e32 v63, v60, v63
	v_mov_b32_e32 v64, v57
	v_mov_b32_e32 v65, v61
	v_add_f32_e32 v62, v57, v62
	v_add_f32_e32 v63, v61, v63
	s_and_b64 vcc, exec, s[4:5]
	v_add_f32_e32 v62, v75, v62
	v_add_f32_e32 v62, v62, v63
	v_mbcnt_lo_u32_b32 v63, -1, 0
	v_mbcnt_hi_u32_b32 v63, -1, v63
	s_nop 0
	v_lshlrev_b32_e32 v63, 2, v63
	v_xor_b32_e32 v64, 0x80, v63
	ds_bpermute_b32 v64, v64, v62
	s_waitcnt lgkmcnt(0)
	v_add_f32_e32 v62, v62, v64
	v_xor_b32_e32 v64, 64, v63
	ds_bpermute_b32 v64, v64, v62
	s_waitcnt lgkmcnt(0)
	v_add_f32_e32 v62, v62, v64
	v_xor_b32_e32 v64, 32, v63
	ds_bpermute_b32 v64, v64, v62
	s_waitcnt lgkmcnt(0)
	v_add_f32_e32 v62, v62, v64
	v_xor_b32_e32 v64, 16, v63
	ds_bpermute_b32 v64, v64, v62
	s_waitcnt lgkmcnt(0)
	v_add_f32_e32 v62, v62, v64
	v_xor_b32_e32 v64, 8, v63
	ds_bpermute_b32 v64, v64, v62
	v_xor_b32_e32 v63, 4, v63
	s_waitcnt lgkmcnt(0)
	v_add_f32_e32 v62, v62, v64
	ds_bpermute_b32 v63, v63, v62
	s_waitcnt lgkmcnt(0)
	v_add_f32_e32 v62, v62, v63
	v_fmamk_f32 v47, v62, 0xba800000, v47
	v_fmamk_f32 v51, v62, 0xba800000, v51
	v_fmac_f32_e32 v46, 0xba800000, v62
	v_mul_f32_e32 v63, v47, v47
	v_fmac_f32_e32 v50, 0xba800000, v62
	v_mul_f32_e32 v64, v51, v51
	v_fmamk_f32 v48, v62, 0xba800000, v48
	v_fmac_f32_e32 v63, v46, v46
	v_fmamk_f32 v52, v62, 0xba800000, v52
	v_fmac_f32_e32 v64, v50, v50
	v_fmamk_f32 v49, v62, 0xba800000, v49
	v_fmac_f32_e32 v63, v48, v48
	v_fmamk_f32 v53, v62, 0xba800000, v53
	v_fmac_f32_e32 v64, v52, v52
	v_fmac_f32_e32 v63, v49, v49
	v_fmac_f32_e32 v64, v53, v53
	v_fmamk_f32 v55, v62, 0xba800000, v55
	v_add_f32_e32 v63, v63, v64
	v_fmac_f32_e32 v54, 0xba800000, v62
	v_mul_f32_e32 v64, v55, v55
	v_fmamk_f32 v59, v62, 0xba800000, v59
	v_fmamk_f32 v57, v62, 0xba800000, v57
	v_fmamk_f32 v56, v62, 0xba800000, v56
	v_fmac_f32_e32 v64, v54, v54
	v_fmamk_f32 v61, v62, 0xba800000, v61
	v_fmamk_f32 v60, v62, 0xba800000, v60
	v_fmac_f32_e32 v58, 0xba800000, v62
	v_mul_f32_e32 v62, v59, v59
	v_fmac_f32_e32 v64, v56, v56
	v_fmac_f32_e32 v62, v58, v58
	v_fmac_f32_e32 v64, v57, v57
	v_fmac_f32_e32 v62, v60, v60
	v_add_f32_e32 v63, v64, v63
	v_fmac_f32_e32 v62, v61, v61
	v_add_f32_e32 v62, v62, v63
	v_mbcnt_lo_u32_b32 v63, -1, 0
	v_mbcnt_hi_u32_b32 v63, -1, v63
	s_nop 0
	v_lshlrev_b32_e32 v63, 2, v63
	v_xor_b32_e32 v64, 0x80, v63
	ds_bpermute_b32 v64, v64, v62
	s_waitcnt lgkmcnt(0)
	v_add_f32_e32 v62, v62, v64
	v_xor_b32_e32 v64, 64, v63
	ds_bpermute_b32 v64, v64, v62
	s_waitcnt lgkmcnt(0)
	v_add_f32_e32 v62, v62, v64
	v_xor_b32_e32 v64, 32, v63
	ds_bpermute_b32 v64, v64, v62
	s_waitcnt lgkmcnt(0)
	v_add_f32_e32 v62, v62, v64
	v_xor_b32_e32 v64, 16, v63
	ds_bpermute_b32 v64, v64, v62
	s_waitcnt lgkmcnt(0)
	v_add_f32_e32 v62, v62, v64
	v_xor_b32_e32 v64, 8, v63
	ds_bpermute_b32 v64, v64, v62
	v_xor_b32_e32 v63, 4, v63
	s_waitcnt lgkmcnt(0)
	v_add_f32_e32 v62, v62, v64
	ds_bpermute_b32 v63, v63, v62
	s_cbranch_vccnz .LBB0_7
	s_waitcnt lgkmcnt(0)
	v_add_f32_e32 v62, v62, v63
	v_fmamk_f32 v62, v62, 0x3a800000, v82
	v_mul_f32_e32 v63, 0x4b800000, v62
	v_cmp_gt_f32_e32 vcc, s17, v62
	v_ashrrev_i32_e32 v75, 31, v74
	s_nop 0
	v_cndmask_b32_e32 v62, v62, v63, vcc
	v_rsq_f32_e32 v64, v62
	v_lshlrev_b64 v[62:63], 11, v[74:75]
	v_mul_f32_e32 v65, 0x45800000, v64
	v_cndmask_b32_e32 v64, v64, v65, vcc
	v_pk_mul_f32 v[52:53], v[52:53], v[64:65] op_sel_hi:[1,0]
	v_pk_mul_f32 v[50:51], v[50:51], v[64:65] op_sel_hi:[1,0]
	v_pk_mul_f32 v[48:49], v[48:49], v[64:65] op_sel_hi:[1,0]
	v_pk_mul_f32 v[46:47], v[46:47], v[64:65] op_sel_hi:[1,0]
	v_pk_mul_f32 v[60:61], v[60:61], v[64:65] op_sel_hi:[1,0]
	v_pk_mul_f32 v[58:59], v[58:59], v[64:65] op_sel_hi:[1,0]
	v_pk_mul_f32 v[56:57], v[56:57], v[64:65] op_sel_hi:[1,0]
	v_pk_mul_f32 v[54:55], v[54:55], v[64:65] op_sel_hi:[1,0]
	v_pk_fma_f32 v[50:51], v[2:3], v[50:51], v[6:7]
	v_pk_fma_f32 v[52:53], v[4:5], v[52:53], v[8:9]
	v_pk_fma_f32 v[64:65], v[10:11], v[46:47], v[14:15]
	v_pk_fma_f32 v[46:47], v[12:13], v[48:49], v[16:17]
	v_pk_fma_f32 v[58:59], v[18:19], v[58:59], v[22:23]
	v_pk_fma_f32 v[60:61], v[20:21], v[60:61], v[24:25]
	v_pk_fma_f32 v[54:55], v[26:27], v[54:55], v[30:31]
	v_pk_fma_f32 v[56:57], v[28:29], v[56:57], v[32:33]
	v_cvt_pk_bf16_f32 v49, v52, v53
	v_cvt_pk_bf16_f32 v48, v50, v51
	v_cvt_pk_bf16_f32 v47, v46, v47
	v_cvt_pk_bf16_f32 v46, v64, v65
	v_lshl_add_u64 v[50:51], v[72:73], 0, v[62:63]
	global_store_dwordx4 v[50:51], v[46:49], off
	s_nop 1
	v_cvt_pk_bf16_f32 v49, v60, v61
	v_cvt_pk_bf16_f32 v48, v58, v59
	v_cvt_pk_bf16_f32 v47, v56, v57
	v_cvt_pk_bf16_f32 v46, v54, v55
	global_store_dwordx4 v[50:51], v[46:49], off offset:1024
	s_branch .LBB0_7

; DI float bflo(uint32_t u) { return __uint_as_float(u << 16); }
; DI float bfhi(uint32_t u) { return __uint_as_float(u & 0xffff0000u); }
; template <int SRC, bool Q8, bool OUTF>
; DI void ln_rows(const void* __restrict__ srcv, const u16* res, u16* dstb, uint32_t* __restrict__ dstq, float* __restrict__ xsc, float* __restrict__ dstf,
;                 const float* __restrict__ g, const float* __restrict__ b, int nrows, const int WAVE_S) {
;     ...
;       const u16* sp = (const u16*)srcv + (size_t)row * DM + 8 * lane;
;       const u16* rp = res + (size_t)row * DM + 8 * lane;
; #pragma unroll
;       for (int i = 0; i < 2; ++i) { sa[i] = *(const u32x4*)(sp + 512 * i); ra[i] = *(const u32x4*)(rp + 512 * i); }
;     }
;   };
;   auto process = [&](int row, const u32x4 (&sa)[NR], const u32x4 (&ra)[2]) {
;     f32x4 v[4];
;     if (SRC == 0) {
; #pragma unroll
;       for (int q = 0; q < 4; ++q) v[q] = __builtin_bit_cast(f32x4, sa[q]);
;     } else {
; #pragma unroll
;       for (int i = 0; i < 2; ++i)
; #pragma unroll
;         for (int hh = 0; hh < 2; ++hh) {
;           const uint32_t s0 = sa[i][2 * hh], s1 = sa[i][2 * hh + 1], r0 = ra[i][2 * hh], r1 = ra[i][2 * hh + 1];
;           v[2 * i + hh] = (f32x4){ALPHA * bflo(r0) + bflo(s0), ALPHA * bfhi(r0) + bfhi(s0), ALPHA * bflo(r1) + bflo(s1), ALPHA * bfhi(r1) + bfhi(s1)};
;         }
;     }
;     float sum = 0.f;
; #pragma unroll
;     for (int q = 0; q < 4; ++q) sum += v[q][0] + v[q][1] + v[q][2] + v[q][3];
;     const float mu = wave_sum(sum) * (1.f / DM);
;     float sq = 0.f;
; #pragma unroll
;     for (int q = 0; q < 4; ++q) {
;       v[q] -= mu;
;       sq += v[q][0] * v[q][0] + v[q][1] * v[q][1] + v[q][2] * v[q][2] + v[q][3] * v[q][3];
;     }
;     const float rstd = rsqrtf(wave_sum(sq) * (1.f / DM) + 1e-5f);
;     float am = 0.f;
; #pragma unroll
;     for (int q = 0; q < 4; ++q) {
;       v[q] = v[q] * rstd * g4[q] + b4[q];
;       if (Q8) am = fmaxf(am, fmaxf(fmaxf(fabsf(v[q][0]), fabsf(v[q][1])), fmaxf(fabsf(v[q][2]), fabsf(v[q][3]))));
;     }
; #pragma unroll
;     for (int i = 0; i < 2; ++i) {
;       u32x4 w = {pk2(v[2 * i][0], v[2 * i][1]), pk2(v[2 * i][2], v[2 * i][3]), pk2(v[2 * i + 1][0], v[2 * i + 1][1]), pk2(v[2 * i + 1][2], v[2 * i + 1][3])};
;       if (dstb != nullptr) *(u32x4*)(dstb + (size_t)row * DM + 512 * i + 8 * lane) = w;
;     }
.LBB0_318:
	s_waitcnt vmcnt(1)
	v_lshlrev_b32_e32 v78, 16, v46
	v_and_b32_e32 v79, 0xffff0000, v46
	v_lshlrev_b32_e32 v80, 16, v42
	v_and_b32_e32 v81, 0xffff0000, v42
	v_lshlrev_b32_e32 v46, 16, v47
	v_and_b32_e32 v47, 0xffff0000, v47
	v_lshlrev_b32_e32 v42, 16, v43
	v_and_b32_e32 v43, 0xffff0000, v43
	v_pk_fma_f32 v[78:79], v[78:79], s[16:17], v[80:81] op_sel_hi:[1,0,1]
	v_pk_fma_f32 v[42:43], v[46:47], s[16:17], v[42:43] op_sel_hi:[1,0,1]
	v_lshlrev_b32_e32 v46, 16, v48
	v_and_b32_e32 v47, 0xffff0000, v48
	v_lshlrev_b32_e32 v80, 16, v44
	v_and_b32_e32 v81, 0xffff0000, v44
	v_lshlrev_b32_e32 v48, 16, v49
	v_and_b32_e32 v49, 0xffff0000, v49
	v_lshlrev_b32_e32 v44, 16, v45
	v_and_b32_e32 v45, 0xffff0000, v45
	v_pk_fma_f32 v[46:47], v[46:47], s[16:17], v[80:81] op_sel_hi:[1,0,1]
	v_pk_fma_f32 v[44:45], v[48:49], s[16:17], v[44:45] op_sel_hi:[1,0,1]
	s_waitcnt vmcnt(0)
	v_lshlrev_b32_e32 v48, 16, v38
	v_and_b32_e32 v49, 0xffff0000, v38
	v_lshlrev_b32_e32 v80, 16, v34
	v_and_b32_e32 v81, 0xffff0000, v34
	v_lshlrev_b32_e32 v38, 16, v39
	v_and_b32_e32 v39, 0xffff0000, v39
	v_lshlrev_b32_e32 v34, 16, v35
	v_and_b32_e32 v35, 0xffff0000, v35
	v_pk_fma_f32 v[80:81], v[48:49], s[16:17], v[80:81] op_sel_hi:[1,0,1]
	v_pk_fma_f32 v[34:35], v[38:39], s[16:17], v[34:35] op_sel_hi:[1,0,1]
	v_lshlrev_b32_e32 v38, 16, v40
	v_and_b32_e32 v39, 0xffff0000, v40
	v_lshlrev_b32_e32 v48, 16, v36
	v_and_b32_e32 v49, 0xffff0000, v36
	v_pk_fma_f32 v[82:83], v[38:39], s[16:17], v[48:49] op_sel_hi:[1,0,1]
	v_lshlrev_b32_e32 v38, 16, v41
	v_and_b32_e32 v39, 0xffff0000, v41
	v_lshlrev_b32_e32 v36, 16, v37
	v_and_b32_e32 v37, 0xffff0000, v37
	v_pk_fma_f32 v[36:37], v[38:39], s[16:17], v[36:37] op_sel_hi:[1,0,1]
	v_add_f32_e32 v38, v46, v47
	v_add_f32_e32 v39, v78, v79
	v_add_f32_e32 v38, v44, v38
	v_add_f32_e32 v39, v42, v39
	v_add_f32_e32 v38, v45, v38
	v_add_f32_e32 v39, v43, v39
	v_add_u32_e32 v74, s64, v76
	v_add_f32_e32 v0, 0, v39
	v_add_f32_e32 v0, v38, v0
	v_min_i32_e32 v50, 0xffff, v74
	v_add_f32_e32 v38, v82, v83
	v_add_f32_e32 v39, v80, v81
	v_ashrrev_i32_e32 v51, 31, v50
	v_add_f32_e32 v38, v36, v38
	v_add_f32_e32 v39, v34, v39
	v_mov_b32_e32 v40, v37
	v_mov_b32_e32 v41, v35
	v_lshlrev_b64 v[50:51], 11, v[50:51]
	v_add_f32_e32 v38, v37, v38
	v_add_f32_e32 v39, v35, v39
	v_lshl_add_u64 v[52:53], v[66:67], 0, v[50:51]
	v_lshl_add_u64 v[54:55], v[68:69], 0, v[50:51]
	v_add_f32_e32 v0, v39, v0
	global_load_dwordx4 v[58:61], v[52:53], off
	s_nop 0
	global_load_dwordx4 v[50:53], v[52:53], off offset:1024
	s_nop 0
	global_load_dwordx4 v[62:65], v[54:55], off
	s_nop 0
	global_load_dwordx4 v[54:57], v[54:55], off offset:1024
	v_add_f32_e32 v0, v38, v0
	s_mov_b32 s18, 0x800000
	ds_bpermute_b32 v39, v84, v0
	v_ashrrev_i32_e32 v77, 31, v76
	s_waitcnt lgkmcnt(0)
	v_add_f32_e32 v0, v0, v39
	ds_bpermute_b32 v39, v85, v0
	s_waitcnt lgkmcnt(0)
	v_add_f32_e32 v0, v0, v39
	ds_bpermute_b32 v39, v86, v0
	s_waitcnt lgkmcnt(0)
	v_add_f32_e32 v0, v0, v39
	ds_bpermute_b32 v39, v87, v0
	s_waitcnt lgkmcnt(0)
	v_add_f32_e32 v0, v0, v39
	ds_bpermute_b32 v39, v88, v0
	s_waitcnt lgkmcnt(0)
	v_add_f32_e32 v0, v0, v39
	ds_bpermute_b32 v38, v89, v0
	s_waitcnt lgkmcnt(0)
	v_add_f32_e32 v0, v0, v38
	v_fmamk_f32 v79, v0, 0xba800000, v79
	v_fmamk_f32 v47, v0, 0xba800000, v47
	v_fmac_f32_e32 v78, 0xba800000, v0
	v_fmac_f32_e32 v46, 0xba800000, v0
	v_fmac_f32_e32 v42, 0xba800000, v0
	v_fmac_f32_e32 v44, 0xba800000, v0
	v_mul_f32_e32 v40, v79, v79
	v_mul_f32_e32 v41, v47, v47
	v_fmamk_f32 v43, v0, 0xba800000, v43
	v_fmamk_f32 v45, v0, 0xba800000, v45
	v_fma_f32 v38, v78, v78, v40
	v_fma_f32 v39, v46, v46, v41
	v_fmamk_f32 v81, v0, 0xba800000, v81
	v_fmamk_f32 v83, v0, 0xba800000, v83
	v_fma_f32 v38, v42, v42, v38
	v_fma_f32 v39, v44, v44, v39
	v_fmac_f32_e32 v80, 0xba800000, v0
	v_fmac_f32_e32 v82, 0xba800000, v0
	v_fma_f32 v38, v43, v43, v38
	v_fma_f32 v39, v45, v45, v39
	v_fmac_f32_e32 v34, 0xba800000, v0
	v_fmac_f32_e32 v36, 0xba800000, v0
	v_mul_f32_e32 v48, v83, v83
	v_mul_f32_e32 v49, v81, v81
	v_fmamk_f32 v35, v0, 0xba800000, v35
	v_fmamk_f32 v37, v0, 0xba800000, v37
	v_fma_f32 v40, v82, v82, v48
	v_fma_f32 v41, v80, v80, v49
	v_fma_f32 v40, v36, v36, v40
	v_fma_f32 v41, v34, v34, v41
	v_mov_b32_e32 v48, v37
	v_mov_b32_e32 v49, v35
	v_fma_f32 v40, v37, v37, v40
	v_fma_f32 v41, v35, v35, v41
	v_add_f32_e32 v0, v38, v39
	v_add_f32_e32 v0, v41, v0
	v_add_f32_e32 v0, v40, v0
	ds_bpermute_b32 v39, v84, v0
	s_waitcnt lgkmcnt(0)
	v_add_f32_e32 v0, v0, v39
	ds_bpermute_b32 v39, v85, v0
	s_waitcnt lgkmcnt(0)
	v_add_f32_e32 v0, v0, v39
	ds_bpermute_b32 v39, v86, v0
	s_waitcnt lgkmcnt(0)
	v_add_f32_e32 v0, v0, v39
	ds_bpermute_b32 v39, v87, v0
	s_waitcnt lgkmcnt(0)
	v_add_f32_e32 v0, v0, v39
	ds_bpermute_b32 v39, v88, v0
	s_waitcnt lgkmcnt(0)
	v_add_f32_e32 v0, v0, v39
	ds_bpermute_b32 v38, v89, v0
	s_waitcnt lgkmcnt(0)
	v_add_f32_e32 v0, v0, v38
	v_fmamk_f32 v0, v0, 0x3a800000, v147
	v_mul_f32_e32 v38, 0x4b800000, v0
	v_cmp_gt_f32_e32 vcc, s18, v0
	v_readlane_b32 s18, v165, 62
	v_readlane_b32 s19, v165, 63
	v_cndmask_b32_e32 v0, v0, v38, vcc
	v_rsq_f32_e32 v0, v0
	s_nop 0
	v_mul_f32_e32 v38, 0x45800000, v0
	v_cndmask_b32_e32 v0, v0, v38, vcc
	v_pk_mul_f32 v[38:39], v[78:79], v[0:1] op_sel_hi:[1,0]
	v_pk_mul_f32 v[40:41], v[42:43], v[0:1] op_sel_hi:[1,0]
	v_pk_fma_f32 v[78:79], v[6:7], v[38:39], v[14:15]
	v_pk_fma_f32 v[48:49], v[8:9], v[40:41], v[16:17]
	v_pk_mul_f32 v[38:39], v[46:47], v[0:1] op_sel_hi:[1,0]
	v_pk_mul_f32 v[40:41], v[44:45], v[0:1] op_sel_hi:[1,0]
	v_pk_fma_f32 v[44:45], v[2:3], v[38:39], v[10:11]
	v_pk_fma_f32 v[42:43], v[4:5], v[40:41], v[12:13]
	v_pk_mul_f32 v[38:39], v[80:81], v[0:1] op_sel_hi:[1,0]
	v_pk_mul_f32 v[34:35], v[34:35], v[0:1] op_sel_hi:[1,0]
	v_pk_mul_f32 v[40:41], v[82:83], v[0:1] op_sel_hi:[1,0]
	v_pk_mul_f32 v[36:37], v[36:37], v[0:1] op_sel_hi:[1,0]
	v_cndmask_b32_e64 v0, 0, 1, s[18:19]
	v_pk_fma_f32 v[34:35], v[24:25], v[34:35], v[32:33]
	v_pk_fma_f32 v[38:39], v[22:23], v[38:39], v[30:31]
	v_pk_fma_f32 v[36:37], v[20:21], v[36:37], v[28:29]
	v_pk_fma_f32 v[40:41], v[18:19], v[40:41], v[26:27]
	v_cmp_ne_u32_e64 s[36:37], 1, v0
	s_andn2_b64 vcc, exec, s[18:19]
	s_cbranch_vccnz .LBB0_320
	v_lshlrev_b64 v[46:47], 11, v[76:77]
	v_cvt_pk_bf16_f32 v83, v42, v43
	v_cvt_pk_bf16_f32 v82, v44, v45
	v_cvt_pk_bf16_f32 v81, v48, v49
	v_cvt_pk_bf16_f32 v80, v78, v79
	v_lshl_add_u64 v[46:47], v[68:69], 0, v[46:47]
	global_store_dwordx4 v[46:47], v[80:83], off
	s_nop 1
	v_cvt_pk_bf16_f32 v83, v36, v37
	v_cvt_pk_bf16_f32 v82, v40, v41
	v_cvt_pk_bf16_f32 v81, v34, v35
	v_cvt_pk_bf16_f32 v80, v38, v39
	global_store_dwordx4 v[46:47], v[80:83], off offset:1024

; DI float bflo(uint32_t u) { return __uint_as_float(u << 16); }
; DI float bfhi(uint32_t u) { return __uint_as_float(u & 0xffff0000u); }
; template <int SRC, bool Q8, bool OUTF>
; DI void ln_rows(const void* __restrict__ srcv, const u16* res, u16* dstb, uint32_t* __restrict__ dstq, float* __restrict__ xsc, float* __restrict__ dstf,
;                 const float* __restrict__ g, const float* __restrict__ b, int nrows, const int WAVE_S) {
;     ...
;       const u16* sp = (const u16*)srcv + (size_t)row * DM + 8 * lane;
;       const u16* rp = res + (size_t)row * DM + 8 * lane;
; #pragma unroll
;       for (int i = 0; i < 2; ++i) { sa[i] = *(const u32x4*)(sp + 512 * i); ra[i] = *(const u32x4*)(rp + 512 * i); }
;     }
;   };
;   auto process = [&](int row, const u32x4 (&sa)[NR], const u32x4 (&ra)[2]) {
;     f32x4 v[4];
;     if (SRC == 0) {
; #pragma unroll
;       for (int q = 0; q < 4; ++q) v[q] = __builtin_bit_cast(f32x4, sa[q]);
;     } else {
; #pragma unroll
;       for (int i = 0; i < 2; ++i)
; #pragma unroll
;         for (int hh = 0; hh < 2; ++hh) {
;           const uint32_t s0 = sa[i][2 * hh], s1 = sa[i][2 * hh + 1], r0 = ra[i][2 * hh], r1 = ra[i][2 * hh + 1];
;           v[2 * i + hh] = (f32x4){ALPHA * bflo(r0) + bflo(s0), ALPHA * bfhi(r0) + bfhi(s0), ALPHA * bflo(r1) + bflo(s1), ALPHA * bfhi(r1) + bfhi(s1)};
;         }
;     }
;     float sum = 0.f;
; #pragma unroll
;     for (int q = 0; q < 4; ++q) sum += v[q][0] + v[q][1] + v[q][2] + v[q][3];
;     const float mu = wave_sum(sum) * (1.f / DM);
;     float sq = 0.f;
; #pragma unroll
;     for (int q = 0; q < 4; ++q) {
;       v[q] -= mu;
;       sq += v[q][0] * v[q][0] + v[q][1] * v[q][1] + v[q][2] * v[q][2] + v[q][3] * v[q][3];
;     }
;     const float rstd = rsqrtf(wave_sum(sq) * (1.f / DM) + 1e-5f);
;     float am = 0.f;
; #pragma unroll
;     for (int q = 0; q < 4; ++q) {
;       v[q] = v[q] * rstd * g4[q] + b4[q];
;       if (Q8) am = fmaxf(am, fmaxf(fmaxf(fabsf(v[q][0]), fabsf(v[q][1])), fmaxf(fabsf(v[q][2]), fabsf(v[q][3]))));
;     }
; #pragma unroll
;     for (int i = 0; i < 2; ++i) {
;       u32x4 w = {pk2(v[2 * i][0], v[2 * i][1]), pk2(v[2 * i][2], v[2 * i][3]), pk2(v[2 * i + 1][0], v[2 * i + 1][1]), pk2(v[2 * i + 1][2], v[2 * i + 1][3])};
;       if (dstb != nullptr) *(u32x4*)(dstb + (size_t)row * DM + 512 * i + 8 * lane) = w;
;     }
.LBB0_322:
	s_or_b64 exec, exec, s[18:19]
	v_cmp_gt_i32_e32 vcc, s81, v74
	s_mov_b64 s[18:19], -1
	s_and_saveexec_b64 s[46:47], vcc
	s_cbranch_execz .LBB0_317
	v_readlane_b32 s18, v166, 26
	s_waitcnt vmcnt(3)
	v_and_b32_e32 v77, 0xffff0000, v62
	v_lshlrev_b32_e32 v78, 16, v58
	v_add_u32_e32 v0, s18, v76
	v_lshlrev_b32_e32 v76, 16, v62
	v_and_b32_e32 v79, 0xffff0000, v58
	v_lshlrev_b32_e32 v62, 16, v63
	v_and_b32_e32 v63, 0xffff0000, v63
	v_lshlrev_b32_e32 v58, 16, v59
	v_and_b32_e32 v59, 0xffff0000, v59
	v_pk_fma_f32 v[76:77], v[76:77], s[16:17], v[78:79] op_sel_hi:[1,0,1]
	v_pk_fma_f32 v[58:59], v[62:63], s[16:17], v[58:59] op_sel_hi:[1,0,1]
	v_lshlrev_b32_e32 v62, 16, v64
	v_and_b32_e32 v63, 0xffff0000, v64
	v_lshlrev_b32_e32 v78, 16, v60
	v_and_b32_e32 v79, 0xffff0000, v60
	v_lshlrev_b32_e32 v64, 16, v65
	v_and_b32_e32 v65, 0xffff0000, v65
	v_lshlrev_b32_e32 v60, 16, v61
	v_and_b32_e32 v61, 0xffff0000, v61
	v_pk_fma_f32 v[62:63], v[62:63], s[16:17], v[78:79] op_sel_hi:[1,0,1]
	v_pk_fma_f32 v[60:61], v[64:65], s[16:17], v[60:61] op_sel_hi:[1,0,1]
	s_waitcnt vmcnt(2)
	v_lshlrev_b32_e32 v64, 16, v54
	v_and_b32_e32 v65, 0xffff0000, v54
	v_lshlrev_b32_e32 v78, 16, v50
	v_and_b32_e32 v79, 0xffff0000, v50
	v_lshlrev_b32_e32 v54, 16, v55
	v_and_b32_e32 v55, 0xffff0000, v55
	v_lshlrev_b32_e32 v50, 16, v51
	v_and_b32_e32 v51, 0xffff0000, v51
	v_pk_fma_f32 v[64:65], v[64:65], s[16:17], v[78:79] op_sel_hi:[1,0,1]
	v_pk_fma_f32 v[50:51], v[54:55], s[16:17], v[50:51] op_sel_hi:[1,0,1]
	v_lshlrev_b32_e32 v54, 16, v56
	v_and_b32_e32 v55, 0xffff0000, v56
	v_lshlrev_b32_e32 v78, 16, v52
	v_and_b32_e32 v79, 0xffff0000, v52
	v_pk_fma_f32 v[80:81], v[54:55], s[16:17], v[78:79] op_sel_hi:[1,0,1]
	v_lshlrev_b32_e32 v54, 16, v57
	v_and_b32_e32 v55, 0xffff0000, v57
	v_lshlrev_b32_e32 v52, 16, v53
	v_and_b32_e32 v53, 0xffff0000, v53
	v_pk_fma_f32 v[52:53], v[54:55], s[16:17], v[52:53] op_sel_hi:[1,0,1]
	v_add_f32_e32 v54, v62, v63
	v_add_f32_e32 v55, v76, v77
	v_add_f32_e32 v54, v60, v54
	v_add_f32_e32 v55, v58, v55
	v_add_f32_e32 v54, v61, v54
	v_add_f32_e32 v55, v59, v55
	v_min_i32_e32 v34, 0xffff, v0
	v_add_f32_e32 v0, 0, v55
	v_add_f32_e32 v0, v54, v0
	v_add_f32_e32 v54, v80, v81
	v_add_f32_e32 v55, v64, v65
	v_ashrrev_i32_e32 v35, 31, v34
	v_add_f32_e32 v54, v52, v54
	v_add_f32_e32 v55, v50, v55
	v_mov_b32_e32 v56, v53
	v_mov_b32_e32 v57, v51
	v_lshlrev_b64 v[34:35], 11, v[34:35]
	v_add_f32_e32 v54, v53, v54
	v_add_f32_e32 v55, v51, v55
	v_lshl_add_u64 v[36:37], v[66:67], 0, v[34:35]
	v_lshl_add_u64 v[38:39], v[68:69], 0, v[34:35]
	v_add_f32_e32 v0, v0, v55
	global_load_dwordx4 v[42:45], v[36:37], off
	s_nop 0
	global_load_dwordx4 v[34:37], v[36:37], off offset:1024
	s_nop 0
	global_load_dwordx4 v[46:49], v[38:39], off
	s_nop 0
	global_load_dwordx4 v[38:41], v[38:39], off offset:1024
	v_add_f32_e32 v0, v54, v0
	s_mov_b32 s18, 0x800000
	ds_bpermute_b32 v55, v84, v0
	v_ashrrev_i32_e32 v75, 31, v74
	s_waitcnt lgkmcnt(0)
	v_add_f32_e32 v0, v0, v55
	ds_bpermute_b32 v55, v85, v0
	s_waitcnt lgkmcnt(0)
	v_add_f32_e32 v0, v0, v55
	ds_bpermute_b32 v55, v86, v0
	s_waitcnt lgkmcnt(0)
	v_add_f32_e32 v0, v0, v55
	ds_bpermute_b32 v55, v87, v0
	s_waitcnt lgkmcnt(0)
	v_add_f32_e32 v0, v0, v55
	ds_bpermute_b32 v55, v88, v0
	s_waitcnt lgkmcnt(0)
	v_add_f32_e32 v0, v0, v55
	ds_bpermute_b32 v54, v89, v0
	s_waitcnt lgkmcnt(0)
	v_add_f32_e32 v0, v0, v54
	v_fmamk_f32 v77, v0, 0xba800000, v77
	v_fmamk_f32 v63, v0, 0xba800000, v63
	v_fmac_f32_e32 v76, 0xba800000, v0
	v_fmac_f32_e32 v62, 0xba800000, v0
	v_fmac_f32_e32 v58, 0xba800000, v0
	v_fmac_f32_e32 v60, 0xba800000, v0
	v_mul_f32_e32 v56, v77, v77
	v_mul_f32_e32 v57, v63, v63
	v_fmamk_f32 v59, v0, 0xba800000, v59
	v_fmamk_f32 v61, v0, 0xba800000, v61
	v_fma_f32 v54, v76, v76, v56
	v_fma_f32 v55, v62, v62, v57
	v_fmamk_f32 v65, v0, 0xba800000, v65
	v_fmamk_f32 v81, v0, 0xba800000, v81
	v_fma_f32 v54, v58, v58, v54
	v_fma_f32 v55, v60, v60, v55
	v_fmac_f32_e32 v64, 0xba800000, v0
	v_fmac_f32_e32 v80, 0xba800000, v0
	v_fma_f32 v54, v59, v59, v54
	v_fma_f32 v55, v61, v61, v55
	v_fmac_f32_e32 v50, 0xba800000, v0
	v_fmac_f32_e32 v52, 0xba800000, v0
	v_mul_f32_e32 v78, v81, v81
	v_mul_f32_e32 v79, v65, v65
	v_fmamk_f32 v51, v0, 0xba800000, v51
	v_fmamk_f32 v53, v0, 0xba800000, v53
	v_fma_f32 v56, v80, v80, v78
	v_fma_f32 v57, v64, v64, v79
	v_fma_f32 v56, v52, v52, v56
	v_fma_f32 v57, v50, v50, v57
	v_mov_b32_e32 v78, v53
	v_mov_b32_e32 v79, v51
	v_fma_f32 v56, v53, v53, v56
	v_fma_f32 v57, v51, v51, v57
	v_add_f32_e32 v0, v54, v55
	v_add_f32_e32 v0, v57, v0
	v_add_f32_e32 v0, v56, v0
	ds_bpermute_b32 v55, v84, v0
	s_waitcnt lgkmcnt(0)
	v_add_f32_e32 v0, v0, v55
	ds_bpermute_b32 v55, v85, v0
	s_waitcnt lgkmcnt(0)
	v_add_f32_e32 v0, v0, v55
	ds_bpermute_b32 v55, v86, v0
	s_waitcnt lgkmcnt(0)
	v_add_f32_e32 v0, v0, v55
	ds_bpermute_b32 v55, v87, v0
	s_waitcnt lgkmcnt(0)
	v_add_f32_e32 v0, v0, v55
	ds_bpermute_b32 v55, v88, v0
	s_waitcnt lgkmcnt(0)
	v_add_f32_e32 v0, v0, v55
	ds_bpermute_b32 v54, v89, v0
	s_waitcnt lgkmcnt(0)
	v_add_f32_e32 v0, v0, v54
	v_fmamk_f32 v0, v0, 0x3a800000, v147
	v_mul_f32_e32 v54, 0x4b800000, v0
	v_cmp_gt_f32_e32 vcc, s18, v0
	s_nop 1
	v_cndmask_b32_e32 v0, v0, v54, vcc
	v_rsq_f32_e32 v0, v0
	s_nop 0
	v_mul_f32_e32 v54, 0x45800000, v0
	v_cndmask_b32_e32 v0, v0, v54, vcc
	v_pk_mul_f32 v[54:55], v[76:77], v[0:1] op_sel_hi:[1,0]
	v_pk_mul_f32 v[56:57], v[58:59], v[0:1] op_sel_hi:[1,0]
	v_pk_fma_f32 v[78:79], v[6:7], v[54:55], v[14:15]
	v_pk_fma_f32 v[76:77], v[8:9], v[56:57], v[16:17]
	v_pk_mul_f32 v[54:55], v[62:63], v[0:1] op_sel_hi:[1,0]
	v_pk_mul_f32 v[56:57], v[60:61], v[0:1] op_sel_hi:[1,0]
	v_pk_fma_f32 v[60:61], v[2:3], v[54:55], v[10:11]
	v_pk_fma_f32 v[58:59], v[4:5], v[56:57], v[12:13]
	v_pk_mul_f32 v[54:55], v[64:65], v[0:1] op_sel_hi:[1,0]
	v_pk_mul_f32 v[50:51], v[50:51], v[0:1] op_sel_hi:[1,0]
	v_pk_mul_f32 v[56:57], v[80:81], v[0:1] op_sel_hi:[1,0]
	v_pk_mul_f32 v[52:53], v[52:53], v[0:1] op_sel_hi:[1,0]
	v_pk_fma_f32 v[50:51], v[24:25], v[50:51], v[32:33]
	v_pk_fma_f32 v[54:55], v[22:23], v[54:55], v[30:31]
	v_pk_fma_f32 v[52:53], v[20:21], v[52:53], v[28:29]
	v_pk_fma_f32 v[56:57], v[18:19], v[56:57], v[26:27]
	s_and_b64 vcc, exec, s[36:37]
	s_cbranch_vccnz .LBB0_325
	v_lshlrev_b64 v[80:81], 11, v[74:75]
	v_cvt_pk_bf16_f32 v65, v58, v59
	v_cvt_pk_bf16_f32 v64, v60, v61
	v_cvt_pk_bf16_f32 v63, v76, v77
	v_cvt_pk_bf16_f32 v62, v78, v79
	v_lshl_add_u64 v[80:81], v[68:69], 0, v[80:81]
	global_store_dwordx4 v[80:81], v[62:65], off
	s_nop 1
	v_cvt_pk_bf16_f32 v65, v52, v53
	v_cvt_pk_bf16_f32 v64, v56, v57
	v_cvt_pk_bf16_f32 v63, v50, v51
	v_cvt_pk_bf16_f32 v62, v54, v55
	global_store_dwordx4 v[80:81], v[62:65], off offset:1024

; DI float bflo(uint32_t u) { return __uint_as_float(u << 16); }
; DI float bfhi(uint32_t u) { return __uint_as_float(u & 0xffff0000u); }
; template <int SRC, bool Q8, bool OUTF>
; DI void ln_rows(const void* __restrict__ srcv, const u16* res, u16* dstb, uint32_t* __restrict__ dstq, float* __restrict__ xsc, float* __restrict__ dstf,
;                 const float* __restrict__ g, const float* __restrict__ b, int nrows, const int WAVE_S) {
;     ...
;       const u16* sp = (const u16*)srcv + (size_t)row * DM + 8 * lane;
;       const u16* rp = res + (size_t)row * DM + 8 * lane;
; #pragma unroll
;       for (int i = 0; i < 2; ++i) { sa[i] = *(const u32x4*)(sp + 512 * i); ra[i] = *(const u32x4*)(rp + 512 * i); }
;     }
;   };
;   auto process = [&](int row, const u32x4 (&sa)[NR], const u32x4 (&ra)[2]) {
;     f32x4 v[4];
;     if (SRC == 0) {
; #pragma unroll
;       for (int q = 0; q < 4; ++q) v[q] = __builtin_bit_cast(f32x4, sa[q]);
;     } else {
; #pragma unroll
;       for (int i = 0; i < 2; ++i)
; #pragma unroll
;         for (int hh = 0; hh < 2; ++hh) {
;           const uint32_t s0 = sa[i][2 * hh], s1 = sa[i][2 * hh + 1], r0 = ra[i][2 * hh], r1 = ra[i][2 * hh + 1];
;           v[2 * i + hh] = (f32x4){ALPHA * bflo(r0) + bflo(s0), ALPHA * bfhi(r0) + bfhi(s0), ALPHA * bflo(r1) + bflo(s1), ALPHA * bfhi(r1) + bfhi(s1)};
;         }
;     }
;     float sum = 0.f;
; #pragma unroll
;     for (int q = 0; q < 4; ++q) sum += v[q][0] + v[q][1] + v[q][2] + v[q][3];
;     const float mu = wave_sum(sum) * (1.f / DM);
;     float sq = 0.f;
; #pragma unroll
;     for (int q = 0; q < 4; ++q) {
;       v[q] -= mu;
;       sq += v[q][0] * v[q][0] + v[q][1] * v[q][1] + v[q][2] * v[q][2] + v[q][3] * v[q][3];
;     }
;     const float rstd = rsqrtf(wave_sum(sq) * (1.f / DM) + 1e-5f);
;     float am = 0.f;
; #pragma unroll
;     for (int q = 0; q < 4; ++q) {
;       v[q] = v[q] * rstd * g4[q] + b4[q];
;       if (Q8) am = fmaxf(am, fmaxf(fmaxf(fabsf(v[q][0]), fabsf(v[q][1])), fmaxf(fabsf(v[q][2]), fabsf(v[q][3]))));
;     }
; #pragma unroll
;     for (int i = 0; i < 2; ++i) {
;       u32x4 w = {pk2(v[2 * i][0], v[2 * i][1]), pk2(v[2 * i][2], v[2 * i][3]), pk2(v[2 * i + 1][0], v[2 * i + 1][1]), pk2(v[2 * i + 1][2], v[2 * i + 1][3])};
;       if (dstb != nullptr) *(u32x4*)(dstb + (size_t)row * DM + 512 * i + 8 * lane) = w;
;     }
.LBB0_637:
	s_waitcnt vmcnt(1)
	v_lshlrev_b32_e32 v78, 16, v46
	v_and_b32_e32 v79, 0xffff0000, v46
	v_lshlrev_b32_e32 v80, 16, v42
	v_and_b32_e32 v81, 0xffff0000, v42
	v_lshlrev_b32_e32 v46, 16, v47
	v_and_b32_e32 v47, 0xffff0000, v47
	v_lshlrev_b32_e32 v42, 16, v43
	v_and_b32_e32 v43, 0xffff0000, v43
	v_pk_fma_f32 v[78:79], v[78:79], s[16:17], v[80:81] op_sel_hi:[1,0,1]
	v_pk_fma_f32 v[46:47], v[46:47], s[16:17], v[42:43] op_sel_hi:[1,0,1]
	v_lshlrev_b32_e32 v42, 16, v48
	v_and_b32_e32 v43, 0xffff0000, v48
	v_lshlrev_b32_e32 v80, 16, v44
	v_and_b32_e32 v81, 0xffff0000, v44
	v_lshlrev_b32_e32 v48, 16, v49
	v_and_b32_e32 v49, 0xffff0000, v49
	v_lshlrev_b32_e32 v44, 16, v45
	v_and_b32_e32 v45, 0xffff0000, v45
	v_pk_fma_f32 v[42:43], v[42:43], s[16:17], v[80:81] op_sel_hi:[1,0,1]
	v_pk_fma_f32 v[48:49], v[48:49], s[16:17], v[44:45] op_sel_hi:[1,0,1]
	s_waitcnt vmcnt(0)
	v_lshlrev_b32_e32 v44, 16, v38
	v_and_b32_e32 v45, 0xffff0000, v38
	v_lshlrev_b32_e32 v80, 16, v34
	v_and_b32_e32 v81, 0xffff0000, v34
	v_lshlrev_b32_e32 v38, 16, v39
	v_and_b32_e32 v39, 0xffff0000, v39
	v_lshlrev_b32_e32 v34, 16, v35
	v_and_b32_e32 v35, 0xffff0000, v35
	v_pk_fma_f32 v[82:83], v[38:39], s[16:17], v[34:35] op_sel_hi:[1,0,1]
	v_lshlrev_b32_e32 v34, 16, v40
	v_and_b32_e32 v35, 0xffff0000, v40
	v_lshlrev_b32_e32 v38, 16, v36
	v_and_b32_e32 v39, 0xffff0000, v36
	v_pk_fma_f32 v[44:45], v[44:45], s[16:17], v[80:81] op_sel_hi:[1,0,1]
	v_pk_fma_f32 v[80:81], v[34:35], s[16:17], v[38:39] op_sel_hi:[1,0,1]
	v_lshlrev_b32_e32 v34, 16, v41
	v_and_b32_e32 v35, 0xffff0000, v41
	v_lshlrev_b32_e32 v36, 16, v37
	v_and_b32_e32 v37, 0xffff0000, v37
	v_pk_fma_f32 v[84:85], v[34:35], s[16:17], v[36:37] op_sel_hi:[1,0,1]
	v_add_f32_e32 v34, v42, v43
	v_add_f32_e32 v35, v78, v79
	v_add_f32_e32 v34, v48, v34
	v_add_f32_e32 v35, v46, v35
	v_add_f32_e32 v34, v49, v34
	v_add_f32_e32 v35, v47, v35
	v_add_u32_e32 v74, s64, v76
	v_add_f32_e32 v0, 0, v35
	v_add_f32_e32 v0, v34, v0
	v_min_i32_e32 v50, 0xffff, v74
	v_add_f32_e32 v34, v80, v81
	v_add_f32_e32 v35, v44, v45
	v_ashrrev_i32_e32 v51, 31, v50
	v_add_f32_e32 v34, v84, v34
	v_add_f32_e32 v35, v82, v35
	v_mov_b32_e32 v36, v85
	v_mov_b32_e32 v37, v83
	v_lshlrev_b64 v[50:51], 11, v[50:51]
	v_add_f32_e32 v34, v85, v34
	v_add_f32_e32 v35, v83, v35
	v_lshl_add_u64 v[52:53], v[66:67], 0, v[50:51]
	v_lshl_add_u64 v[54:55], v[68:69], 0, v[50:51]
	v_add_f32_e32 v0, v35, v0
	global_load_dwordx4 v[58:61], v[52:53], off
	s_nop 0
	global_load_dwordx4 v[50:53], v[52:53], off offset:1024
	s_nop 0
	global_load_dwordx4 v[62:65], v[54:55], off
	s_nop 0
	global_load_dwordx4 v[54:57], v[54:55], off offset:1024
	v_add_f32_e32 v0, v34, v0
	v_mbcnt_lo_u32_b32 v34, -1, 0
	v_mbcnt_hi_u32_b32 v34, -1, v34
	s_mov_b32 s18, 0x800000
	v_lshlrev_b32_e32 v34, 2, v34
	v_xor_b32_e32 v35, 0x80, v34
	ds_bpermute_b32 v35, v35, v0
	v_ashrrev_i32_e32 v77, 31, v76
	s_waitcnt lgkmcnt(0)
	v_add_f32_e32 v0, v0, v35
	v_xor_b32_e32 v35, 64, v34
	ds_bpermute_b32 v35, v35, v0
	s_waitcnt lgkmcnt(0)
	v_add_f32_e32 v0, v0, v35
	v_xor_b32_e32 v35, 32, v34
	ds_bpermute_b32 v35, v35, v0
	s_waitcnt lgkmcnt(0)
	v_add_f32_e32 v0, v0, v35
	v_xor_b32_e32 v35, 16, v34
	ds_bpermute_b32 v35, v35, v0
	s_waitcnt lgkmcnt(0)
	v_add_f32_e32 v0, v0, v35
	v_xor_b32_e32 v35, 8, v34
	ds_bpermute_b32 v35, v35, v0
	v_xor_b32_e32 v34, 4, v34
	s_waitcnt lgkmcnt(0)
	v_add_f32_e32 v0, v0, v35
	ds_bpermute_b32 v34, v34, v0
	s_waitcnt lgkmcnt(0)
	v_add_f32_e32 v0, v0, v34
	v_fmamk_f32 v79, v0, 0xba800000, v79
	v_fmamk_f32 v43, v0, 0xba800000, v43
	v_fmac_f32_e32 v78, 0xba800000, v0
	v_fmac_f32_e32 v42, 0xba800000, v0
	v_fmac_f32_e32 v46, 0xba800000, v0
	v_fmac_f32_e32 v48, 0xba800000, v0
	v_mul_f32_e32 v36, v79, v79
	v_mul_f32_e32 v37, v43, v43
	v_fmamk_f32 v47, v0, 0xba800000, v47
	v_fmamk_f32 v49, v0, 0xba800000, v49
	v_fma_f32 v34, v78, v78, v36
	v_fma_f32 v35, v42, v42, v37
	v_fmamk_f32 v45, v0, 0xba800000, v45
	v_fmamk_f32 v81, v0, 0xba800000, v81
	v_fma_f32 v34, v46, v46, v34
	v_fma_f32 v35, v48, v48, v35
	v_fmac_f32_e32 v44, 0xba800000, v0
	v_fmac_f32_e32 v80, 0xba800000, v0
	v_fma_f32 v34, v47, v47, v34
	v_fma_f32 v35, v49, v49, v35
	v_fmac_f32_e32 v82, 0xba800000, v0
	v_fmac_f32_e32 v84, 0xba800000, v0
	v_mul_f32_e32 v38, v81, v81
	v_mul_f32_e32 v39, v45, v45
	v_fmamk_f32 v83, v0, 0xba800000, v83
	v_fmamk_f32 v85, v0, 0xba800000, v85
	v_fma_f32 v36, v80, v80, v38
	v_fma_f32 v37, v44, v44, v39
	v_fma_f32 v36, v84, v84, v36
	v_fma_f32 v37, v82, v82, v37
	v_mov_b32_e32 v38, v85
	v_mov_b32_e32 v39, v83
	v_fma_f32 v36, v85, v85, v36
	v_fma_f32 v37, v83, v83, v37
	v_add_f32_e32 v0, v34, v35
	v_mbcnt_lo_u32_b32 v34, -1, 0
	v_mbcnt_hi_u32_b32 v34, -1, v34
	v_add_f32_e32 v0, v37, v0
	v_lshlrev_b32_e32 v34, 2, v34
	v_add_f32_e32 v0, v36, v0
	v_xor_b32_e32 v35, 0x80, v34
	ds_bpermute_b32 v35, v35, v0
	s_waitcnt lgkmcnt(0)
	v_add_f32_e32 v0, v0, v35
	v_xor_b32_e32 v35, 64, v34
	ds_bpermute_b32 v35, v35, v0
	s_waitcnt lgkmcnt(0)
	v_add_f32_e32 v0, v0, v35
	v_xor_b32_e32 v35, 32, v34
	ds_bpermute_b32 v35, v35, v0
	s_waitcnt lgkmcnt(0)
	v_add_f32_e32 v0, v0, v35
	v_xor_b32_e32 v35, 16, v34
	ds_bpermute_b32 v35, v35, v0
	s_waitcnt lgkmcnt(0)
	v_add_f32_e32 v0, v0, v35
	v_xor_b32_e32 v35, 8, v34
	ds_bpermute_b32 v35, v35, v0
	v_xor_b32_e32 v34, 4, v34
	s_waitcnt lgkmcnt(0)
	v_add_f32_e32 v0, v0, v35
	ds_bpermute_b32 v34, v34, v0
	s_waitcnt lgkmcnt(0)
	v_add_f32_e32 v0, v0, v34
	v_fmamk_f32 v0, v0, 0x3a800000, v147
	v_mul_f32_e32 v34, 0x4b800000, v0
	v_cmp_gt_f32_e32 vcc, s18, v0
	s_nop 1
	v_cndmask_b32_e32 v0, v0, v34, vcc
	v_rsq_f32_e32 v0, v0
	s_nop 0
	v_mul_f32_e32 v34, 0x45800000, v0
	v_cndmask_b32_e32 v0, v0, v34, vcc
	v_pk_mul_f32 v[34:35], v[78:79], v[0:1] op_sel_hi:[1,0]
	v_pk_mul_f32 v[36:37], v[46:47], v[0:1] op_sel_hi:[1,0]
	v_pk_mul_f32 v[38:39], v[42:43], v[0:1] op_sel_hi:[1,0]
	v_pk_mul_f32 v[40:41], v[48:49], v[0:1] op_sel_hi:[1,0]
	v_pk_mul_f32 v[42:43], v[44:45], v[0:1] op_sel_hi:[1,0]
	v_pk_mul_f32 v[44:45], v[82:83], v[0:1] op_sel_hi:[1,0]
	v_pk_mul_f32 v[46:47], v[80:81], v[0:1] op_sel_hi:[1,0]
	v_pk_mul_f32 v[48:49], v[84:85], v[0:1] op_sel_hi:[1,0]
	v_pk_fma_f32 v[36:37], v[8:9], v[36:37], v[16:17]
	v_pk_fma_f32 v[34:35], v[6:7], v[34:35], v[14:15]
	v_pk_fma_f32 v[40:41], v[4:5], v[40:41], v[12:13]
	v_pk_fma_f32 v[38:39], v[2:3], v[38:39], v[10:11]
	v_pk_fma_f32 v[44:45], v[24:25], v[44:45], v[32:33]
	v_pk_fma_f32 v[42:43], v[22:23], v[42:43], v[30:31]
	v_pk_fma_f32 v[48:49], v[20:21], v[48:49], v[28:29]
	v_pk_fma_f32 v[46:47], v[18:19], v[46:47], v[26:27]
	s_and_b64 vcc, exec, s[40:41]
	s_cbranch_vccz .LBB0_639
; template <int SRC, bool Q8, bool OUTF>
; DI void ln_rows(const void* __restrict__ srcv, const u16* res, u16* dstb, uint32_t* __restrict__ dstq, float* __restrict__ xsc, float* __restrict__ dstf,
;                 const float* __restrict__ g, const float* __restrict__ b, int nrows, const int WAVE_S) {
;     ...
; #pragma unroll
;     for (int i = 0; i < 2; ++i) {
;       u32x4 w = {pk2(v[2 * i][0], v[2 * i][1]), pk2(v[2 * i][2], v[2 * i][3]), pk2(v[2 * i + 1][0], v[2 * i + 1][1]), pk2(v[2 * i + 1][2], v[2 * i + 1][3])};
;       if (dstb != nullptr) *(u32x4*)(dstb + (size_t)row * DM + 512 * i + 8 * lane) = w;
;     }
	v_lshlrev_b64 v[82:83], 11, v[76:77]
	v_cvt_pk_bf16_f32 v81, v40, v41
	v_cvt_pk_bf16_f32 v80, v38, v39
	v_cvt_pk_bf16_f32 v79, v36, v37
	v_cvt_pk_bf16_f32 v78, v34, v35
	v_lshl_add_u64 v[84:85], v[70:71], 0, v[82:83]
	global_store_dwordx4 v[84:85], v[78:81], off
	v_lshl_add_u64 v[82:83], v[68:69], 0, v[82:83]
	s_nop 0
	v_cvt_pk_bf16_f32 v81, v48, v49
	v_cvt_pk_bf16_f32 v80, v46, v47
	v_cvt_pk_bf16_f32 v79, v44, v45
	v_cvt_pk_bf16_f32 v78, v42, v43
	global_store_dwordx4 v[82:83], v[78:81], off offset:1024

; DI float bflo(uint32_t u) { return __uint_as_float(u << 16); }
; DI float bfhi(uint32_t u) { return __uint_as_float(u & 0xffff0000u); }
; template <int SRC, bool Q8, bool OUTF>
; DI void ln_rows(const void* __restrict__ srcv, const u16* res, u16* dstb, uint32_t* __restrict__ dstq, float* __restrict__ xsc, float* __restrict__ dstf,
;                 const float* __restrict__ g, const float* __restrict__ b, int nrows, const int WAVE_S) {
;     ...
;       const u16* sp = (const u16*)srcv + (size_t)row * DM + 8 * lane;
;       const u16* rp = res + (size_t)row * DM + 8 * lane;
; #pragma unroll
;       for (int i = 0; i < 2; ++i) { sa[i] = *(const u32x4*)(sp + 512 * i); ra[i] = *(const u32x4*)(rp + 512 * i); }
;     }
;   };
;   auto process = [&](int row, const u32x4 (&sa)[NR], const u32x4 (&ra)[2]) {
;     f32x4 v[4];
;     if (SRC == 0) {
; #pragma unroll
;       for (int q = 0; q < 4; ++q) v[q] = __builtin_bit_cast(f32x4, sa[q]);
;     } else {
; #pragma unroll
;       for (int i = 0; i < 2; ++i)
; #pragma unroll
;         for (int hh = 0; hh < 2; ++hh) {
;           const uint32_t s0 = sa[i][2 * hh], s1 = sa[i][2 * hh + 1], r0 = ra[i][2 * hh], r1 = ra[i][2 * hh + 1];
;           v[2 * i + hh] = (f32x4){ALPHA * bflo(r0) + bflo(s0), ALPHA * bfhi(r0) + bfhi(s0), ALPHA * bflo(r1) + bflo(s1), ALPHA * bfhi(r1) + bfhi(s1)};
;         }
;     }
;     float sum = 0.f;
; #pragma unroll
;     for (int q = 0; q < 4; ++q) sum += v[q][0] + v[q][1] + v[q][2] + v[q][3];
;     const float mu = wave_sum(sum) * (1.f / DM);
;     float sq = 0.f;
; #pragma unroll
;     for (int q = 0; q < 4; ++q) {
;       v[q] -= mu;
;       sq += v[q][0] * v[q][0] + v[q][1] * v[q][1] + v[q][2] * v[q][2] + v[q][3] * v[q][3];
;     }
;     const float rstd = rsqrtf(wave_sum(sq) * (1.f / DM) + 1e-5f);
;     float am = 0.f;
; #pragma unroll
;     for (int q = 0; q < 4; ++q) {
;       v[q] = v[q] * rstd * g4[q] + b4[q];
;       if (Q8) am = fmaxf(am, fmaxf(fmaxf(fabsf(v[q][0]), fabsf(v[q][1])), fmaxf(fabsf(v[q][2]), fabsf(v[q][3]))));
;     }
; #pragma unroll
;     for (int i = 0; i < 2; ++i) {
;       u32x4 w = {pk2(v[2 * i][0], v[2 * i][1]), pk2(v[2 * i][2], v[2 * i][3]), pk2(v[2 * i + 1][0], v[2 * i + 1][1]), pk2(v[2 * i + 1][2], v[2 * i + 1][3])};
;       if (dstb != nullptr) *(u32x4*)(dstb + (size_t)row * DM + 512 * i + 8 * lane) = w;
;     }
.LBB0_641:
	v_cmp_gt_i32_e32 vcc, s81, v74
	s_mov_b64 s[18:19], -1
	s_and_saveexec_b64 s[46:47], vcc
	s_cbranch_execz .LBB0_636
	v_readlane_b32 s18, v166, 26
	s_waitcnt vmcnt(1)
	v_and_b32_e32 v77, 0xffff0000, v62
	v_lshlrev_b32_e32 v78, 16, v58
	v_add_u32_e32 v0, s18, v76
	v_lshlrev_b32_e32 v76, 16, v62
	v_and_b32_e32 v79, 0xffff0000, v58
	v_lshlrev_b32_e32 v62, 16, v63
	v_and_b32_e32 v63, 0xffff0000, v63
	v_lshlrev_b32_e32 v58, 16, v59
	v_and_b32_e32 v59, 0xffff0000, v59
	v_pk_fma_f32 v[76:77], v[76:77], s[16:17], v[78:79] op_sel_hi:[1,0,1]
	v_pk_fma_f32 v[62:63], v[62:63], s[16:17], v[58:59] op_sel_hi:[1,0,1]
	v_lshlrev_b32_e32 v58, 16, v64
	v_and_b32_e32 v59, 0xffff0000, v64
	v_lshlrev_b32_e32 v78, 16, v60
	v_and_b32_e32 v79, 0xffff0000, v60
	v_lshlrev_b32_e32 v64, 16, v65
	v_and_b32_e32 v65, 0xffff0000, v65
	v_lshlrev_b32_e32 v60, 16, v61
	v_and_b32_e32 v61, 0xffff0000, v61
	v_pk_fma_f32 v[58:59], v[58:59], s[16:17], v[78:79] op_sel_hi:[1,0,1]
	v_pk_fma_f32 v[64:65], v[64:65], s[16:17], v[60:61] op_sel_hi:[1,0,1]
	s_waitcnt vmcnt(0)
	v_lshlrev_b32_e32 v60, 16, v54
	v_and_b32_e32 v61, 0xffff0000, v54
	v_lshlrev_b32_e32 v78, 16, v50
	v_and_b32_e32 v79, 0xffff0000, v50
	v_lshlrev_b32_e32 v54, 16, v55
	v_and_b32_e32 v55, 0xffff0000, v55
	v_lshlrev_b32_e32 v50, 16, v51
	v_and_b32_e32 v51, 0xffff0000, v51
	v_pk_fma_f32 v[80:81], v[54:55], s[16:17], v[50:51] op_sel_hi:[1,0,1]
	v_lshlrev_b32_e32 v50, 16, v56
	v_and_b32_e32 v51, 0xffff0000, v56
	v_lshlrev_b32_e32 v54, 16, v52
	v_and_b32_e32 v55, 0xffff0000, v52
	v_pk_fma_f32 v[60:61], v[60:61], s[16:17], v[78:79] op_sel_hi:[1,0,1]
	v_pk_fma_f32 v[78:79], v[50:51], s[16:17], v[54:55] op_sel_hi:[1,0,1]
	v_lshlrev_b32_e32 v50, 16, v57
	v_and_b32_e32 v51, 0xffff0000, v57
	v_lshlrev_b32_e32 v52, 16, v53
	v_and_b32_e32 v53, 0xffff0000, v53
	v_pk_fma_f32 v[82:83], v[50:51], s[16:17], v[52:53] op_sel_hi:[1,0,1]
	v_add_f32_e32 v50, v58, v59
	v_add_f32_e32 v51, v76, v77
	v_add_f32_e32 v50, v64, v50
	v_add_f32_e32 v51, v62, v51
	v_add_f32_e32 v50, v65, v50
	v_add_f32_e32 v51, v63, v51
	v_min_i32_e32 v34, 0xffff, v0
	v_add_f32_e32 v0, 0, v51
	v_add_f32_e32 v0, v50, v0
	v_add_f32_e32 v50, v78, v79
	v_add_f32_e32 v51, v60, v61
	v_ashrrev_i32_e32 v35, 31, v34
	v_add_f32_e32 v50, v82, v50
	v_add_f32_e32 v51, v80, v51
	v_mov_b32_e32 v52, v83
	v_mov_b32_e32 v53, v81
	v_lshlrev_b64 v[34:35], 11, v[34:35]
	v_add_f32_e32 v50, v83, v50
	v_add_f32_e32 v51, v81, v51
	v_lshl_add_u64 v[36:37], v[66:67], 0, v[34:35]
	v_lshl_add_u64 v[38:39], v[68:69], 0, v[34:35]
	v_add_f32_e32 v0, v0, v51
	global_load_dwordx4 v[42:45], v[36:37], off
	s_nop 0
	global_load_dwordx4 v[34:37], v[36:37], off offset:1024
	s_nop 0
	global_load_dwordx4 v[46:49], v[38:39], off
	s_nop 0
	global_load_dwordx4 v[38:41], v[38:39], off offset:1024
	v_add_f32_e32 v0, v50, v0
	v_mbcnt_lo_u32_b32 v50, -1, 0
	v_mbcnt_hi_u32_b32 v50, -1, v50
	s_mov_b32 s18, 0x800000
	v_lshlrev_b32_e32 v50, 2, v50
	v_xor_b32_e32 v51, 0x80, v50
	ds_bpermute_b32 v51, v51, v0
	v_ashrrev_i32_e32 v75, 31, v74
	s_waitcnt lgkmcnt(0)
	v_add_f32_e32 v0, v0, v51
	v_xor_b32_e32 v51, 64, v50
	ds_bpermute_b32 v51, v51, v0
	s_waitcnt lgkmcnt(0)
	v_add_f32_e32 v0, v0, v51
	v_xor_b32_e32 v51, 32, v50
	ds_bpermute_b32 v51, v51, v0
	s_waitcnt lgkmcnt(0)
	v_add_f32_e32 v0, v0, v51
	v_xor_b32_e32 v51, 16, v50
	ds_bpermute_b32 v51, v51, v0
	s_waitcnt lgkmcnt(0)
	v_add_f32_e32 v0, v0, v51
	v_xor_b32_e32 v51, 8, v50
	ds_bpermute_b32 v51, v51, v0
	v_xor_b32_e32 v50, 4, v50
	s_waitcnt lgkmcnt(0)
	v_add_f32_e32 v0, v0, v51
	ds_bpermute_b32 v50, v50, v0
	s_waitcnt lgkmcnt(0)
	v_add_f32_e32 v0, v0, v50
	v_fmamk_f32 v77, v0, 0xba800000, v77
	v_fmamk_f32 v59, v0, 0xba800000, v59
	v_fmac_f32_e32 v76, 0xba800000, v0
	v_fmac_f32_e32 v58, 0xba800000, v0
	v_fmac_f32_e32 v62, 0xba800000, v0
	v_fmac_f32_e32 v64, 0xba800000, v0
	v_mul_f32_e32 v52, v77, v77
	v_mul_f32_e32 v53, v59, v59
	v_fmamk_f32 v63, v0, 0xba800000, v63
	v_fmamk_f32 v65, v0, 0xba800000, v65
	v_fma_f32 v50, v76, v76, v52
	v_fma_f32 v51, v58, v58, v53
	v_fmamk_f32 v61, v0, 0xba800000, v61
	v_fmamk_f32 v79, v0, 0xba800000, v79
	v_fma_f32 v50, v62, v62, v50
	v_fma_f32 v51, v64, v64, v51
	v_fmac_f32_e32 v60, 0xba800000, v0
	v_fmac_f32_e32 v78, 0xba800000, v0
	v_fma_f32 v50, v63, v63, v50
	v_fma_f32 v51, v65, v65, v51
	v_fmac_f32_e32 v80, 0xba800000, v0
	v_fmac_f32_e32 v82, 0xba800000, v0
	v_mul_f32_e32 v54, v79, v79
	v_mul_f32_e32 v55, v61, v61
	v_fmamk_f32 v81, v0, 0xba800000, v81
	v_fmamk_f32 v83, v0, 0xba800000, v83
	v_fma_f32 v52, v78, v78, v54
	v_fma_f32 v53, v60, v60, v55
	v_fma_f32 v52, v82, v82, v52
	v_fma_f32 v53, v80, v80, v53
	v_mov_b32_e32 v54, v83
	v_mov_b32_e32 v55, v81
	v_fma_f32 v52, v83, v83, v52
	v_fma_f32 v53, v81, v81, v53
	v_add_f32_e32 v0, v50, v51
	v_mbcnt_lo_u32_b32 v50, -1, 0
	v_mbcnt_hi_u32_b32 v50, -1, v50
	v_add_f32_e32 v0, v53, v0
	v_lshlrev_b32_e32 v50, 2, v50
	v_add_f32_e32 v0, v52, v0
	v_xor_b32_e32 v51, 0x80, v50
	ds_bpermute_b32 v51, v51, v0
	s_waitcnt lgkmcnt(0)
	v_add_f32_e32 v0, v0, v51
	v_xor_b32_e32 v51, 64, v50
	ds_bpermute_b32 v51, v51, v0
	s_waitcnt lgkmcnt(0)
	v_add_f32_e32 v0, v0, v51
	v_xor_b32_e32 v51, 32, v50
	ds_bpermute_b32 v51, v51, v0
	s_waitcnt lgkmcnt(0)
	v_add_f32_e32 v0, v0, v51
	v_xor_b32_e32 v51, 16, v50
	ds_bpermute_b32 v51, v51, v0
	s_waitcnt lgkmcnt(0)
	v_add_f32_e32 v0, v0, v51
	v_xor_b32_e32 v51, 8, v50
	ds_bpermute_b32 v51, v51, v0
	v_xor_b32_e32 v50, 4, v50
	s_waitcnt lgkmcnt(0)
	v_add_f32_e32 v0, v0, v51
	ds_bpermute_b32 v50, v50, v0
	s_waitcnt lgkmcnt(0)
	v_add_f32_e32 v0, v0, v50
	v_fmamk_f32 v0, v0, 0x3a800000, v147
	v_mul_f32_e32 v50, 0x4b800000, v0
	v_cmp_gt_f32_e32 vcc, s18, v0
	s_nop 1
	v_cndmask_b32_e32 v0, v0, v50, vcc
	v_rsq_f32_e32 v0, v0
	s_nop 0
	v_mul_f32_e32 v50, 0x45800000, v0
	v_cndmask_b32_e32 v0, v0, v50, vcc
	v_pk_mul_f32 v[50:51], v[76:77], v[0:1] op_sel_hi:[1,0]
	v_pk_mul_f32 v[52:53], v[62:63], v[0:1] op_sel_hi:[1,0]
	v_pk_mul_f32 v[54:55], v[58:59], v[0:1] op_sel_hi:[1,0]
	v_pk_mul_f32 v[56:57], v[64:65], v[0:1] op_sel_hi:[1,0]
	v_pk_mul_f32 v[58:59], v[60:61], v[0:1] op_sel_hi:[1,0]
	v_pk_mul_f32 v[60:61], v[80:81], v[0:1] op_sel_hi:[1,0]
	v_pk_mul_f32 v[62:63], v[78:79], v[0:1] op_sel_hi:[1,0]
	v_pk_mul_f32 v[64:65], v[82:83], v[0:1] op_sel_hi:[1,0]
	v_pk_fma_f32 v[52:53], v[8:9], v[52:53], v[16:17]
	v_pk_fma_f32 v[50:51], v[6:7], v[50:51], v[14:15]
	v_pk_fma_f32 v[56:57], v[4:5], v[56:57], v[12:13]
	v_pk_fma_f32 v[54:55], v[2:3], v[54:55], v[10:11]
	v_pk_fma_f32 v[60:61], v[24:25], v[60:61], v[32:33]
	v_pk_fma_f32 v[58:59], v[22:23], v[58:59], v[30:31]
	v_pk_fma_f32 v[64:65], v[20:21], v[64:65], v[28:29]
	v_pk_fma_f32 v[62:63], v[18:19], v[62:63], v[26:27]
	s_and_b64 vcc, exec, s[40:41]
	s_cbranch_vccz .LBB0_644
; template <int SRC, bool Q8, bool OUTF>
; DI void ln_rows(const void* __restrict__ srcv, const u16* res, u16* dstb, uint32_t* __restrict__ dstq, float* __restrict__ xsc, float* __restrict__ dstf,
;                 const float* __restrict__ g, const float* __restrict__ b, int nrows, const int WAVE_S) {
;     ...
; #pragma unroll
;     for (int i = 0; i < 2; ++i) {
;       u32x4 w = {pk2(v[2 * i][0], v[2 * i][1]), pk2(v[2 * i][2], v[2 * i][3]), pk2(v[2 * i + 1][0], v[2 * i + 1][1]), pk2(v[2 * i + 1][2], v[2 * i + 1][3])};
;       if (dstb != nullptr) *(u32x4*)(dstb + (size_t)row * DM + 512 * i + 8 * lane) = w;
;     }
	v_lshlrev_b64 v[80:81], 11, v[74:75]
	v_cvt_pk_bf16_f32 v79, v56, v57
	v_cvt_pk_bf16_f32 v78, v54, v55
	v_cvt_pk_bf16_f32 v77, v52, v53
	v_cvt_pk_bf16_f32 v76, v50, v51
	v_lshl_add_u64 v[82:83], v[70:71], 0, v[80:81]
	global_store_dwordx4 v[82:83], v[76:79], off
	v_lshl_add_u64 v[80:81], v[68:69], 0, v[80:81]
	s_nop 0
	v_cvt_pk_bf16_f32 v79, v64, v65
	v_cvt_pk_bf16_f32 v78, v62, v63
	v_cvt_pk_bf16_f32 v77, v60, v61
	v_cvt_pk_bf16_f32 v76, v58, v59
	global_store_dwordx4 v[80:81], v[76:79], off offset:1024
